# GPRIO-old: NOPRIO plus one static s_setprio 1 for waves 0-3 at every GEMM tile-loop entry (reset at phase end)
# speedup vs baseline: 1.0009x; 1.0009x over previous
; template <class Epi, class Sched>
; __device__ __forceinline__ void gemm_phase(PG8_LAS unsigned char* lds, const Gemm g, const Sched& S, const Epi& E, int tid_in) {
;     ...
;     Unit cur, nxt; int ui = 0;
;     if (!S.next(0, cur)) return;
.LBB0_255:
	v_readfirstlane_b32 s100, v240
	s_nop 3
	s_lshr_b32 s100, s100, 6
	s_cmp_gt_u32 s100, 3
	s_cbranch_scc1 .Lgprio_255
	s_setprio 1

; template <class Epi, class Sched>
; __device__ __forceinline__ void gemm_phase(PG8_LAS unsigned char* lds, const Gemm g, const Sched& S, const Epi& E, int tid_in) {
;     ...
;     Unit cur, nxt; int ui = 0;
;     if (!S.next(0, cur)) return;
.LBB0_379:
	s_andn2_b64 vcc, exec, s[2:3]
	s_cbranch_vccnz .LBB0_415
	v_readfirstlane_b32 s100, v240
	s_nop 3
	s_lshr_b32 s100, s100, 6
	s_cmp_gt_u32 s100, 3
	s_cbranch_scc1 .Lgprio_380
	s_setprio 1
